# layer-0 mixer: all weight-conversion jobs of the phase now run on the GDN-chain blocks after their chains; MLA-side blocks skip them
# speedup vs baseline: 1.0891x; 1.0067x over previous
; DI void convert_weights(const P& p, int layer, char* smem, int vb, int nvb, int part) {
;     ...
;   for (int job = vb; job < total; job += nvb) {
;     int j = part == 0 ? (job < 3 * nFF ? job : job + 3 * nFF)
;                       : (job < 3 * nFF ? job + 3 * nFF : 6 * nFF + nIn + nQ + nKV + (job - 3 * nFF));
; __global__ void __launch_bounds__(NTHR, 2) mega(P p) {
;     ...
;         __syncthreads();
;         convert_weights(p, 0, smem, svb, snvb, 1);
;         convert_weights(p, 1, smem, svb, snvb, 0);
.LBB0_1106:
	s_branch .LBB0_1108
	v_readlane_b32 s0, v220, 45
	v_readlane_b32 s1, v220, 46
	s_andn2_b64 vcc, exec, s[0:1]
	v_readlane_b32 s40, v218, 17
	s_waitcnt vmcnt(63) expcnt(7) lgkmcnt(15)
	s_barrier
	s_cbranch_vccz .LBB0_1112
.LBB0_1107:
	v_readlane_b32 s0, v220, 51
	v_readlane_b32 s1, v220, 52
	s_andn2_b64 vcc, exec, s[0:1]
	v_readlane_b32 s15, v218, 17
	s_add_i32 s15, s15, 0x100
	s_cbranch_vccz .LBB0_1156

; __global__ void __launch_bounds__(NTHR, 2) mega(P p) {
;     ...
;       if (!split0 || vb < 256)
;         for (int cid = vb; cid < 256; cid += (split0 ? 256 : nvb)) gdn_chain(p, cid, smem);
;       __syncthreads();
;       if (!split0 || vb >= 256) {
;         XcdBarrier& bs = split0 ? xb2 : xb;
;         {
;           GemmDesc g = gemm_simple((const u16*)(ws + OFF_REGB), EVEN_IN, (const u16*)(ws + OFF_WQUP), 384, T, 768);
;           g.o16 = (u16*)(ws + OFF_QB); g.ldo = 768; g.nreal = 768;
;           gemm_auto<EPI_STORE>(g, T, smem, svb, snvb);
;           GemmDesc g2 = gemm_simple((const u16*)(ws + OFF_REGB) + 384, EVEN_IN, (const u16*)(ws + OFF_WKVUP), 256, T, 1024);
;           g2.o16 = (u16*)(ws + OFF_REGA); g2.ldo = 1024; g2.nreal = 1024;
;           gemm_auto<EPI_STORE>(g2, T, smem, svb, snvb);
;         }
;         xcd_barrier(bs);
;         mla_finalize(p, smem, svb, snvb);
;         xcd_barrier(bs);
;         const u16* Q = (const u16*)(ws + OFF_QB);
;         const u16* Kb = (const u16*)(ws + OFF_KB);
;         const u16* KV = (const u16*)(ws + OFF_REGA);
;         for (int it = svb; it < 1024 + 128; it += snvb) {
;           if (it < 1024) {
;             const int b = it >> 7, h = (it >> 4) & 7, qt = it & 15;
;             attn_item<96, false>(Q, 768, h * 96, Kb, 768, h * 96, KV, 1024, h * 128 + 64, b * SEQ + qt * 128, qt * 128,
;                                  LAT + b * CTXL, b * SEQ, 0, 32, 0.f, (u16*)(ws + OFF_QB), 768, h * 96, smem);
;           } else {
;             const int j = it - 1024;
;             const int b = j >> 4, h = (j >> 1) & 7, qt = j & 1;
;             attn_item<96, false>(Q, 768, h * 96, Kb, 768, h * 96, KV, 1024, h * 128 + 64, LAT + b * CTXL + qt * 128, 0,
;                                  LAT + b * CTXL, b * SEQ, 0, 0, 0.f, (u16*)(ws + OFF_QB), 768, h * 96, smem);
;           }
;         }
;         __syncthreads();
;         convert_weights(p, 0, smem, svb, snvb, 1);
;         convert_weights(p, 1, smem, svb, snvb, 0);
.Lgdn_conv:
	v_readlane_b32 s40, v218, 17
	s_add_i32 s40, s40, 0x100
	s_branch .LBB0_1112
